# gemm8w256 loops: LDS-DMA issue moved from the MFMA phase into the fragment-read phase, counted waits vmcnt 8/4/0
# speedup vs baseline: 1.0002x; 1.0002x over previous
.LBB0_119:
	s_add_i32 s52, s31, 16
	v_add_u32_e32 v2, s52, v197
	v_add_u32_e32 v132, v2, v198
	v_add_u32_e32 v140, s52, v187
	ds_read_b128 v[160:163], v132 offset:16384
	ds_read_b128 v[156:159], v132 offset:18432
	v_add_u32_e32 v132, v140, v198
	v_add_u32_e32 v2, v2, v199
	ds_read_b128 v[176:179], v132
	ds_read_b128 v[172:175], v132 offset:2048
	ds_read_b128 v[168:171], v132 offset:4096
	ds_read_b128 v[164:167], v132 offset:6144
	ds_read_b128 v[136:139], v2 offset:16384
	ds_read_b128 v[132:135], v2 offset:18432
	v_add_u32_e32 v2, v140, v199
	ds_read_b128 v[152:155], v2
	ds_read_b128 v[148:151], v2 offset:2048
	ds_read_b128 v[144:147], v2 offset:4096
	ds_read_b128 v[140:143], v2 offset:6144
	s_cmp_gt_u32 s57, 28
	s_cbranch_scc1 .Lmvd0_nodma
	s_add_i32 s52, s25, 16
	v_add_u32_e32 v2, s52, v185
	v_lshl_add_u64 v[226:227], v[194:195], 0, s[36:37]
	v_readfirstlane_b32 s52, v2
	v_lshl_add_u64 v[228:229], v[192:193], 0, s[36:37]
	s_mov_b32 m0, s52
	v_lshl_add_u64 v[230:231], v[190:191], 0, s[36:37]
	global_load_lds_dwordx4 v[226:227], off
	s_add_u32 m0, s52, 0x400
	v_lshl_add_u64 v[232:233], v[188:189], 0, s[36:37]
	global_load_lds_dwordx4 v[228:229], off
	s_add_u32 m0, s52, 0x4000
	s_nop 0
	global_load_lds_dwordx4 v[230:231], off
	s_add_u32 m0, s52, 0x4400
	s_nop 0
	global_load_lds_dwordx4 v[232:233], off
	s_waitcnt vmcnt(8) lgkmcnt(0)
	s_branch .LBB0_123
.Lmvd0_nodma:
	s_cmp_gt_u32 s57, 29
	s_cbranch_scc1 .Lmvd0_w0
	s_waitcnt vmcnt(4) lgkmcnt(0)
	s_branch .LBB0_123
.Lmvd0_w0:
	s_waitcnt vmcnt(0) lgkmcnt(0)
.LBB0_123:
	s_barrier
	s_waitcnt lgkmcnt(0)
	v_mfma_f32_32x32x16_f16 v[116:131], v[160:163], v[176:179], v[116:131]
	v_mfma_f32_32x32x16_f16 v[100:115], v[156:159], v[176:179], v[100:115]
	v_mfma_f32_32x32x16_f16 v[84:99], v[160:163], v[172:175], v[84:99]
	v_mfma_f32_32x32x16_f16 v[68:83], v[156:159], v[172:175], v[68:83]
	v_mfma_f32_32x32x16_f16 v[52:67], v[160:163], v[168:171], v[52:67]
	v_mfma_f32_32x32x16_f16 v[36:51], v[156:159], v[168:171], v[36:51]
	v_mfma_f32_32x32x16_f16 v[20:35], v[160:163], v[164:167], v[20:35]
	v_mfma_f32_32x32x16_f16 v[4:19], v[156:159], v[164:167], v[4:19]
	s_branch .LBB0_118

.LBB0_311:
	s_add_i32 s30, s42, 16
	v_add_u32_e32 v2, s30, v193
	v_add_u32_e32 v132, v2, v194
	v_add_u32_e32 v140, s30, v192
	ds_read_b128 v[160:163], v132 offset:16384
	ds_read_b128 v[156:159], v132 offset:18432
	v_add_u32_e32 v132, v140, v194
	v_add_u32_e32 v2, v2, v195
	ds_read_b128 v[176:179], v132
	ds_read_b128 v[172:175], v132 offset:2048
	ds_read_b128 v[168:171], v132 offset:4096
	ds_read_b128 v[164:167], v132 offset:6144
	ds_read_b128 v[136:139], v2 offset:16384
	ds_read_b128 v[132:135], v2 offset:18432
	v_add_u32_e32 v2, v140, v195
	ds_read_b128 v[152:155], v2
	ds_read_b128 v[148:151], v2 offset:2048
	ds_read_b128 v[144:147], v2 offset:4096
	ds_read_b128 v[140:143], v2 offset:6144
	s_cmp_gt_u32 s36, 28
	s_cbranch_scc1 .Lmvd1_nodma
	s_add_i32 s30, s37, 16
	v_add_u32_e32 v2, s30, v189
	v_lshl_add_u64 v[226:227], v[0:1], 0, s[28:29]
	v_readfirstlane_b32 s30, v2
	v_lshl_add_u64 v[228:229], v[180:181], 0, s[28:29]
	s_mov_b32 m0, s30
	v_lshl_add_u64 v[230:231], v[184:185], 0, s[28:29]
	global_load_lds_dwordx4 v[226:227], off
	s_add_u32 m0, s30, 0x400
	v_lshl_add_u64 v[232:233], v[186:187], 0, s[28:29]
	global_load_lds_dwordx4 v[228:229], off
	s_add_u32 m0, s30, 0x4000
	s_nop 0
	global_load_lds_dwordx4 v[230:231], off
	s_add_u32 m0, s30, 0x4400
	s_nop 0
	global_load_lds_dwordx4 v[232:233], off
	s_waitcnt vmcnt(8) lgkmcnt(0)
	s_branch .LBB0_315
.Lmvd1_nodma:
	s_cmp_gt_u32 s36, 29
	s_cbranch_scc1 .Lmvd1_w0
	s_waitcnt vmcnt(4) lgkmcnt(0)
	s_branch .LBB0_315

.LBB0_315:
	s_barrier
	s_waitcnt lgkmcnt(0)
	v_mfma_f32_32x32x16_f16 v[116:131], v[176:179], v[160:163], v[116:131]
	v_mfma_f32_32x32x16_f16 v[100:115], v[176:179], v[156:159], v[100:115]
	v_mfma_f32_32x32x16_f16 v[84:99], v[172:175], v[160:163], v[84:99]
	v_mfma_f32_32x32x16_f16 v[68:83], v[172:175], v[156:159], v[68:83]
	v_mfma_f32_32x32x16_f16 v[52:67], v[168:171], v[160:163], v[52:67]
	v_mfma_f32_32x32x16_f16 v[36:51], v[168:171], v[156:159], v[36:51]
	v_mfma_f32_32x32x16_f16 v[20:35], v[164:167], v[160:163], v[20:35]
	v_mfma_f32_32x32x16_f16 v[4:19], v[164:167], v[156:159], v[4:19]
	s_branch .LBB0_310

.LBB0_453:
	s_add_i32 s34, s31, 16
	v_add_u32_e32 v2, s34, v192
	v_add_u32_e32 v132, v2, v193
	v_add_u32_e32 v140, s34, v191
	ds_read_b128 v[160:163], v132 offset:16384
	ds_read_b128 v[156:159], v132 offset:18432
	v_add_u32_e32 v132, v140, v193
	v_add_u32_e32 v2, v2, v194
	ds_read_b128 v[176:179], v132
	ds_read_b128 v[172:175], v132 offset:2048
	ds_read_b128 v[168:171], v132 offset:4096
	ds_read_b128 v[164:167], v132 offset:6144
	ds_read_b128 v[136:139], v2 offset:16384
	ds_read_b128 v[132:135], v2 offset:18432
	v_add_u32_e32 v2, v140, v194
	ds_read_b128 v[152:155], v2
	ds_read_b128 v[148:151], v2 offset:2048
	ds_read_b128 v[144:147], v2 offset:4096
	ds_read_b128 v[140:143], v2 offset:6144
	s_cmp_gt_u32 s36, 28
	s_cbranch_scc1 .Lmvd2_nodma
	s_add_i32 s34, s25, 16
	v_add_u32_e32 v2, s34, v1
	v_lshl_add_u64 v[226:227], v[180:181], 0, s[28:29]
	v_readfirstlane_b32 s34, v2
	v_lshl_add_u64 v[228:229], v[184:185], 0, s[28:29]
	s_mov_b32 m0, s34
	v_lshl_add_u64 v[230:231], v[186:187], 0, s[28:29]
	global_load_lds_dwordx4 v[226:227], off
	s_add_u32 m0, s34, 0x400
	v_lshl_add_u64 v[232:233], v[188:189], 0, s[28:29]
	global_load_lds_dwordx4 v[228:229], off
	s_add_u32 m0, s34, 0x4000
	s_nop 0
	global_load_lds_dwordx4 v[230:231], off
	s_add_u32 m0, s34, 0x4400
	s_nop 0
	global_load_lds_dwordx4 v[232:233], off
	s_waitcnt vmcnt(8) lgkmcnt(0)
	s_branch .LBB0_457

.LBB0_733:
	s_add_i32 s52, s56, 16
	v_add_u32_e32 v2, s52, v192
	v_add_u32_e32 v132, v2, v193
	v_add_u32_e32 v140, s52, v181
	ds_read_b128 v[160:163], v132 offset:16384
	ds_read_b128 v[156:159], v132 offset:18432
	v_add_u32_e32 v132, v140, v193
	v_add_u32_e32 v2, v2, v194
	ds_read_b128 v[176:179], v132
	ds_read_b128 v[172:175], v132 offset:2048
	ds_read_b128 v[168:171], v132 offset:4096
	ds_read_b128 v[164:167], v132 offset:6144
	ds_read_b128 v[136:139], v2 offset:16384
	ds_read_b128 v[132:135], v2 offset:18432
	v_add_u32_e32 v2, v140, v194
	ds_read_b128 v[152:155], v2
	ds_read_b128 v[148:151], v2 offset:2048
	ds_read_b128 v[144:147], v2 offset:4096
	ds_read_b128 v[140:143], v2 offset:6144
	s_cmp_gt_u32 s57, 28
	s_cbranch_scc1 .Lmvd3_nodma
	s_add_i32 s52, s55, 16
	v_add_u32_e32 v2, s52, v1
	v_lshl_add_u64 v[226:227], v[190:191], 0, s[36:37]
	v_readfirstlane_b32 s52, v2
	v_lshl_add_u64 v[228:229], v[188:189], 0, s[36:37]
	s_mov_b32 m0, s52
	v_lshl_add_u64 v[230:231], v[186:187], 0, s[36:37]
	global_load_lds_dwordx4 v[226:227], off
	s_add_u32 m0, s52, 0x400
	v_lshl_add_u64 v[232:233], v[184:185], 0, s[36:37]
	global_load_lds_dwordx4 v[228:229], off
	s_add_u32 m0, s52, 0x4000
	s_nop 0
	global_load_lds_dwordx4 v[230:231], off
	s_add_u32 m0, s52, 0x4400
	s_nop 0
	global_load_lds_dwordx4 v[232:233], off
	s_waitcnt vmcnt(8) lgkmcnt(0)
	s_branch .LBB0_737

.LBB0_1125:
	s_add_i32 s44, s49, 16
	v_add_u32_e32 v2, s44, v192
	v_add_u32_e32 v132, v2, v193
	v_add_u32_e32 v140, s44, v191
	ds_read_b128 v[160:163], v132 offset:16384
	ds_read_b128 v[156:159], v132 offset:18432
	v_add_u32_e32 v132, v140, v193
	v_add_u32_e32 v2, v2, v194
	ds_read_b128 v[176:179], v132
	ds_read_b128 v[172:175], v132 offset:2048
	ds_read_b128 v[168:171], v132 offset:4096
	ds_read_b128 v[164:167], v132 offset:6144
	ds_read_b128 v[136:139], v2 offset:16384
	ds_read_b128 v[132:135], v2 offset:18432
	v_add_u32_e32 v2, v140, v194
	ds_read_b128 v[152:155], v2
	ds_read_b128 v[148:151], v2 offset:2048
	ds_read_b128 v[144:147], v2 offset:4096
	ds_read_b128 v[140:143], v2 offset:6144
	s_cmp_gt_u32 s50, 28
	s_cbranch_scc1 .Lmvd4_nodma
	s_add_i32 s44, s48, 16
	v_add_u32_e32 v2, s44, v190
	v_lshl_add_u64 v[226:227], v[188:189], 0, s[42:43]
	v_readfirstlane_b32 s44, v2
	v_lshl_add_u64 v[228:229], v[186:187], 0, s[42:43]
	s_mov_b32 m0, s44
	v_lshl_add_u64 v[230:231], v[184:185], 0, s[42:43]
	global_load_lds_dwordx4 v[226:227], off
	s_add_u32 m0, s44, 0x400
	v_lshl_add_u64 v[232:233], v[180:181], 0, s[42:43]
	global_load_lds_dwordx4 v[228:229], off
	s_add_u32 m0, s44, 0x4000
	s_nop 0
	global_load_lds_dwordx4 v[230:231], off
	s_add_u32 m0, s44, 0x4400
	s_nop 0
	global_load_lds_dwordx4 v[232:233], off
	s_waitcnt vmcnt(8) lgkmcnt(0)
	s_branch .LBB0_1129
.Lmvd4_nodma:
	s_cmp_gt_u32 s50, 29
	s_cbranch_scc1 .Lmvd4_w0
	s_waitcnt vmcnt(4) lgkmcnt(0)
	s_branch .LBB0_1129
